# stagger+deep dense attention, fix-up units in halves with batched carry chain, sample-batch key loads one page ahead (ring), prompt indexer scoring with 4-deep key ring
# speedup vs baseline: 1.0176x; 1.0038x over previous
;     ...
;     unsigned* ctr = (unsigned*)(p.ws + WS_CTR) + ctr_off;
;     for (;;) {
;         const unsigned idx = wq_next(ctr, lds);
;         if (idx >= (unsigned)(MS + LRU_NCHUNK)) break;
;         if (idx < (unsigned)MS) sample_row_unit(p, lds, (int)idx); else lru_fixup_unit(p, (int)idx - MS);
.LBB0_2885:
	s_add_u32 s6, s34, 0x8000
	s_addc_u32 s7, s35, 0
	s_add_u32 s8, s34, 0x33f42200
	s_addc_u32 s9, s35, 0
	s_add_u32 s10, s34, 0x33fc4200
	s_addc_u32 s11, s35, 0
	s_add_u32 s3, s30, 0x6306000
	s_addc_u32 s23, s31, 0
	s_add_u32 s33, s34, 0x344c6200
	s_addc_u32 s46, s35, 0
	s_add_u32 s47, s34, 0x3371a000
	s_addc_u32 s48, s35, 0
	s_add_u32 s12, s30, 0x6308000
	s_addc_u32 s13, s31, 0
	s_add_u32 s14, s30, 0x6348000
	s_addc_u32 s15, s31, 0
	s_add_u32 s16, s34, 0x33fc6200
	v_writelane_b32 v239, s16, 18
	s_addc_u32 s16, s35, 0
	s_add_i32 s51, 0, 0x20c40
	s_waitcnt vmcnt(0)
	v_mbcnt_lo_u32_b32 v2, -1, 0
	s_mov_b64 s[4:5], 0x8000
	s_mov_b32 s17, 0
	v_mov_b32_e32 v11, 0
	v_mov_b32_e32 v1, s51
	s_movk_i32 s77, 0x183
	s_mov_b64 s[18:19], 0x10000
	s_mov_b64 s[36:37], 0x1000
	s_mov_b32 s88, 0x23093000
	s_mov_b32 s89, 0x23095000
	s_mov_b32 s91, 0x23097000
	s_mov_b32 s94, 0x23099000
	s_mov_b32 s95, 0x2309b000
	s_mov_b32 s96, 0x2309d000
	s_mov_b32 s97, 0x2309f000
	s_mov_b32 s49, 0x230a0000
	s_movk_i32 s50, 0x100
	s_movk_i32 s68, 0x1fff
	s_add_i32 s69, 0, 0x8600
	s_mov_b64 s[38:39], 0x80
	s_add_i32 s70, 0, 0x8a00
	s_mov_b32 s71, 0xff800000
	s_mov_b32 s72, 0x3fb8aa3b
	s_mov_b32 s73, 0xc2ce8ed0
	s_mov_b32 s74, 0x42b17218
	s_add_i32 s75, 0, 0x9600
	s_add_i32 s76, 0, 0xbe00
	v_mbcnt_hi_u32_b32 v78, -1, v2
	v_mov_b32_e32 v79, 0x7f800000
	v_writelane_b32 v238, s16, 3
	s_branch .LBB0_2889

; __device__ __forceinline__ int fresh_tid() { int t = threadIdx.x; asm volatile("" : "+v"(t)); return t; }
; __device__ __forceinline__ void lru_fixup_unit(const Params& p, int ck) {
;     const int tid = fresh_tid(), ch = tid * 2;
;     unsigned char* ws = p.ws;
;     const bf16_t* GG = (const bf16_t*)(ws + WS_GG);
;     const float* HL = (const float*)(ws + WS_HL); const float* PP = (const float*)(ws + WS_PP); const float* SUMA = (const float*)(ws + WS_SUMA); const float* SUMH = (const float*)(ws + WS_SUMH);
;     bf16_t* CATB = (bf16_t*)(ws + WS_CATB); float* PS = (float*)(ws + WS_PS);
;     typedef float f32x2 __attribute__((ext_vector_type(2)));
;     f32x2 carry = (f32x2){0.f, 0.f};
;     const bool prompt = ck < LRU_PCHUNK;
;     if (prompt) {
;         const int b = ck / LRU_CPB, kk = ck % LRU_CPB;
; #pragma unroll 16
;         for (int j = 0; j < kk; ++j) {
;             const f32x2 A = *(const f32x2*)(SUMA + (size_t)(b * LRU_CPB + j) * DRNN + ch), Hh = *(const f32x2*)(SUMH + (size_t)(b * LRU_CPB + j) * DRNN + ch);
;             carry = A * carry + Hh;
;         }
;     }
;     ...
;         const unsigned idx = wq_next(ctr, lds);
;         if (idx >= (unsigned)(MS + LRU_NCHUNK)) break;
;         if (idx < (unsigned)MS) sample_row_unit(p, lds, (int)idx); else lru_fixup_unit(p, (int)idx - MS);
.LBB0_2893:
	s_or_b64 exec, exec, s[40:41]
	s_waitcnt lgkmcnt(0)
	s_barrier
	ds_read_b32 v2, v1
	s_mov_b64 s[40:41], -1
	s_waitcnt lgkmcnt(0)
	v_cmp_lt_u32_e32 vcc, s77, v2
	v_readfirstlane_b32 s44, v2
	s_cbranch_vccnz .LBB0_2888
	s_cmpk_gt_u32 s44, 0x7f
	s_cbranch_scc0 .LBB0_2910
	v_mov_b32_e32 v2, v0
	s_add_i32 s40, s44, 0xffffff80
	s_and_b32 s45, s40, 1
	s_lshr_b32 s40, s40, 1
	s_cmpk_gt_u32 s40, 0x7f
	v_lshlrev_b32_e32 v6, 1, v2
	v_mov_b32_e32 v2, 0
	v_mov_b32_e32 v3, 0
	s_cbranch_scc1 .LBB0_2905
	s_and_b32 s16, s40, 63
	s_cmp_eq_u32 s16, 0
	s_cbranch_scc1 .LBB0_2905
	s_and_b32 s41, s40, 64
	s_lshl_b32 s41, s41, 12
	s_add_u32 s78, s8, s41
	s_addc_u32 s79, s9, 0
	s_add_u32 s42, s10, s41
	s_addc_u32 s43, s11, 0
	v_lshlrev_b32_e32 v4, 2, v6

; __device__ __forceinline__ unsigned cvt_pk_bf16(float lo, float hi) { unsigned r; asm volatile("v_cvt_pk_bf16_f32 %0, %1, %2" : "=v"(r) : "v"(lo), "v"(hi)); return r; }
; __device__ __forceinline__ unsigned cvt_pk_bf16(float lo, float hi) { unsigned r; asm volatile("v_cvt_pk_bf16_f32 %0, %1, %2" : "=v"(r) : "v"(lo), "v"(hi)); return r; }
; __device__ __forceinline__ float gelu_tanh(float x) { const float a = -2.3022081985f * (x + 0.044715f * x * x * x); return x * __builtin_amdgcn_rcpf(1.0f + __builtin_amdgcn_exp2f(a)); }
; __device__ __forceinline__ void lru_fixup_unit(const Params& p, int ck) {
;     ...
;     const bool prompt = ck < LRU_PCHUNK;
;     if (prompt) {
;         const int b = ck / LRU_CPB, kk = ck % LRU_CPB;
; #pragma unroll 16
;         for (int j = 0; j < kk; ++j) {
;             const f32x2 A = *(const f32x2*)(SUMA + (size_t)(b * LRU_CPB + j) * DRNN + ch), Hh = *(const f32x2*)(SUMH + (size_t)(b * LRU_CPB + j) * DRNN + ch);
;             carry = A * carry + Hh;
;         }
;     }
; #pragma unroll 1
;     for (int lr0 = 0; lr0 < LRU_CH; lr0 += 16) {
;         f32x2 hl[16], pp[16]; unsigned ggw[16];
; #pragma unroll
;         for (int i = 0; i < 16; ++i) { const size_t grow = (size_t)(ck * LRU_CH + lr0 + i); hl[i] = *(const f32x2*)(HL + grow * DRNN + ch); pp[i] = *(const f32x2*)(PP + grow * DRNN + ch); ggw[i] = *(const unsigned*)(GG + grow * DRNN + ch); }
; #pragma unroll
;         for (int i = 0; i < 16; ++i) {
;             const int lr = lr0 + i; const size_t grow = (size_t)(ck * LRU_CH + lr);
;             const f32x2 gg = (f32x2){gelu_tanh(__uint_as_float(ggw[i] << 16)), gelu_tanh(__uint_as_float(ggw[i] & 0xffff0000u))};
;             const f32x2 h = hl[i] + pp[i] * carry;
;             *(unsigned*)(CATB + grow * D + ch) = cvt_pk_bf16(h.x * gg.x, h.y * gg.y);
;             if (prompt && (ck % LRU_CPB) == LRU_CPB - 1 && lr == LRU_CH - 1) *(f32x2*)(p.out + O_HP + (size_t)(ck / LRU_CPB) * DRNN + ch) = h;
;         }
.LBB0_2905:
	s_lshl_b32 s16, s40, 17
	s_and_b32 s41, s40, 0xbf
	s_cmp_eq_u32 s41, 63
	s_cselect_b64 s[42:43], -1, 0
	s_lshl_b32 s78, s40, 16
	s_lshl_b32 s40, s40, 6
	s_and_b32 s40, s40, 0x1000
	v_ashrrev_i32_e32 v7, 31, v6
	s_add_u32 s40, s3, s40
	s_addc_u32 s41, s23, 0
	v_lshlrev_b64 v[8:9], 2, v[6:7]
	v_lshlrev_b64 v[12:13], 1, v[6:7]
	s_mov_b32 s79, s17
	v_lshl_add_u64 v[4:5], s[40:41], 0, v[8:9]
	v_lshl_add_u64 v[6:7], s[16:17], 1, v[12:13]
	v_lshl_add_u64 v[8:9], s[78:79], 2, v[8:9]
	v_lshl_add_u64 v[12:13], v[12:13], 0, s[16:17]
	s_lshl_b32 s78, s45, 17
	s_mov_b32 s79, 0
	v_lshl_add_u64 v[6:7], v[6:7], 0, s[78:79]
	v_lshl_add_u64 v[8:9], v[8:9], 0, s[78:79]
	s_lshl_b32 s78, s45, 16
	v_lshl_add_u64 v[12:13], v[12:13], 0, s[78:79]
	s_lshl_b32 s16, s45, 5
	s_add_i32 s16, s16, -16
	s_xor_b64 s[40:41], s[42:43], -1
	s_branch .LBB0_2907
.LBB0_2906:
	s_add_i32 s16, s16, 16
	v_lshl_add_u64 v[6:7], v[6:7], 0, s[18:19]
	v_lshl_add_u64 v[8:9], v[8:9], 0, s[18:19]
	s_lshl_b32 s78, s45, 5
	s_add_i32 s78, s78, 15
	s_cmp_gt_u32 s16, s78
	v_lshl_add_u64 v[12:13], v[12:13], 0, s[4:5]
	s_cbranch_scc1 .LBB0_2909
